# A2 loop: bias address math only on near-band tiles; self-max canonicalisations removed from row-max trees
# speedup vs baseline: 1.0097x; 1.0087x over previous
; template <int M>
; __device__ __forceinline__ void qkt_map_roll(f32x16& p0, f32x16& p1, int kb, int qa) {
;   p0 = f32x16{}; p1 = f32x16{};
;   const int a0 = kb ^ ((M << 7) | (0 << 5)); const bf16x8 x0 = lds_rd128<0>(a0), y0 = lds_rd128<8192>(a0); const bf16x8 z0 = (M == 0) ? lds_rd128<0>(qa) : lds_rd128<4096>(qa);
;   const int a1 = kb ^ ((M << 7) | (1 << 5)); const bf16x8 x1 = lds_rd128<0>(a1), y1 = lds_rd128<8192>(a1); const bf16x8 z1 = (M == 0) ? lds_rd128<1024>(qa) : lds_rd128<5120>(qa);
;   asm volatile("s_waitcnt lgkmcnt(3)" ::: "memory"); SBAR();
;   p0 = __builtin_amdgcn_mfma_f32_32x32x16_bf16(x0, z0, p0, 0, 0, 0); p1 = __builtin_amdgcn_mfma_f32_32x32x16_bf16(y0, z0, p1, 0, 0, 0);
;   const int a2 = kb ^ ((M << 7) | (2 << 5)); const bf16x8 x2 = lds_rd128<0>(a2), y2 = lds_rd128<8192>(a2); const bf16x8 z2 = (M == 0) ? lds_rd128<2048>(qa) : lds_rd128<6144>(qa);
;   asm volatile("s_waitcnt lgkmcnt(3)" ::: "memory"); SBAR();
;   p0 = __builtin_amdgcn_mfma_f32_32x32x16_bf16(x1, z1, p0, 0, 0, 0); p1 = __builtin_amdgcn_mfma_f32_32x32x16_bf16(y1, z1, p1, 0, 0, 0);
;   const int a3 = kb ^ ((M << 7) | (3 << 5)); const bf16x8 x3 = lds_rd128<0>(a3), y3 = lds_rd128<8192>(a3); const bf16x8 z3 = (M == 0) ? lds_rd128<3072>(qa) : lds_rd128<7168>(qa);
;   asm volatile("s_waitcnt lgkmcnt(3)" ::: "memory"); SBAR();
;   p0 = __builtin_amdgcn_mfma_f32_32x32x16_bf16(x2, z2, p0, 0, 0, 0); p1 = __builtin_amdgcn_mfma_f32_32x32x16_bf16(y2, z2, p1, 0, 0, 0);
;   asm volatile("s_waitcnt lgkmcnt(0)" ::: "memory"); SBAR();
;   p0 = __builtin_amdgcn_mfma_f32_32x32x16_bf16(x3, z3, p0, 0, 0, 0); p1 = __builtin_amdgcn_mfma_f32_32x32x16_bf16(y3, z3, p1, 0, 0, 0);
;   SBAR();
; __device__ __forceinline__ void attn_unit_A2(const bf16_t* __restrict__ Qb, int ldq, const bf16_t* __restrict__ Kh, int ldk, const bf16_t* __restrict__ Vh, int ldv, int nkeys, int q0, ...
;     ...
;     const int b = j & 1, kt0 = j * KVBLK;
;     const int dlo_ = kt0 - q0 - 255, dhi_ = kt0 + 63 - q0;
;     float cb = 0.f; const bool nearb = !(dlo_ >= 1024) && !(dhi_ <= -1024);
;     if (dlo_ >= 1024) cb = cb_hi; else if (dhi_ <= -1024) cb = cb_lo;
;     const float* tb_ = tbl_l + (kt0 - qlane + TOFF + 4 * hi);
;     f32x16 s0, s1; bf16x8 pa0, pa1, pa2, pa3; float al0, al1;
;     const int vb = vb0 + b * (int)SHM_V;
;     qkt_map_roll<0>(s0, s1, kbA + b * SHM_K, qaA);
;     SBAR();
;     if (nearb) {
; #pragma unroll
.LBB0_335:
	s_add_i32 s6, s61, s11
	s_cmp_lt_i32 s11, s60
	s_cselect_b64 s[8:9], -1, 0
	s_cmpk_gt_i32 s6, 0xfbc1
	s_cselect_b64 s[22:23], -1, 0
	s_and_b32 s64, s62, 0x4000
	v_add_u32_e32 v226, s64, v211
	ds_read_b128 v[2:5], v226 offset:0
	ds_read_b128 v[6:9], v226 offset:0x2000
	ds_read_b128 v[10:13], v208 offset:0
	v_xor_b32_e32 v144, 32, v226
	ds_read_b128 v[228:231], v144 offset:0
	ds_read_b128 v[232:235], v144 offset:0x2000
	ds_read_b128 v[236:239], v208 offset:0x400
	s_waitcnt lgkmcnt(3)
	s_and_b64 s[76:77], s[8:9], s[22:23]
	v_mfma_f32_32x32x16_bf16 v[160:175], v[2:5], v[10:13], 0
	v_mfma_f32_32x32x16_bf16 v[144:159], v[6:9], v[10:13], 0
	v_xor_b32_e32 v10, 64, v226
	ds_read_b128 v[2:5], v10 offset:0
	ds_read_b128 v[6:9], v10 offset:0x2000
	ds_read_b128 v[10:13], v208 offset:0x800
	s_waitcnt lgkmcnt(3)
	v_mfma_f32_32x32x16_bf16 v[160:175], v[228:231], v[236:239], v[160:175]
	v_xor_b32_e32 v192, 0x60, v226
	ds_read_b128 v[228:231], v192 offset:0
	v_mfma_f32_32x32x16_bf16 v[144:159], v[232:235], v[236:239], v[144:159]
	ds_read_b128 v[232:235], v192 offset:0x2000
	ds_read_b128 v[236:239], v208 offset:0xc00
	s_waitcnt lgkmcnt(3)
	v_mfma_f32_32x32x16_bf16 v[160:175], v[2:5], v[10:13], v[160:175]
	s_waitcnt lgkmcnt(0)
	v_mfma_f32_32x32x16_bf16 v[144:159], v[6:9], v[10:13], v[144:159]
	v_mfma_f32_32x32x16_bf16 v[160:175], v[228:231], v[236:239], v[160:175]
	v_mfma_f32_32x32x16_bf16 v[144:159], v[232:235], v[236:239], v[144:159]
	v_cndmask_b32_e64 v2, 0, 1, s[76:77]
	v_cmp_ne_u32_e64 s[6:7], 1, v2
	s_andn2_b64 vcc, exec, s[76:77]
	s_cbranch_vccnz .LBB0_337
	v_add_u32_e32 v15, s63, v217
	v_add_u32_e32 v223, 0x15e00, v15
	v_add_u32_e32 v234, 0x15e80, v15
	v_add_u32_e32 v235, 0x15e08, v15
	v_add_u32_e32 v236, 0x15e88, v15
	v_add_u32_e32 v237, 0x15e20, v15
	v_add_u32_e32 v238, 0x15ea0, v15
	v_add_u32_e32 v239, 0x15e28, v15
	v_add_u32_e32 v240, 0x15ea8, v15
	v_add_u32_e32 v228, 0x15e40, v15
	v_add_u32_e32 v229, 0x15ec0, v15
	v_add_u32_e32 v230, 0x15e48, v15
	v_add_u32_e32 v231, 0x15ec8, v15
	v_add_u32_e32 v232, 0x15e60, v15
	v_add_u32_e32 v224, 0x15ee0, v15
	v_add_u32_e32 v233, 0x15e68, v15
	v_add_u32_e32 v225, 0x15ee8, v15
	ds_read2_b32 v[2:3], v223 offset1:1
	ds_read2_b32 v[4:5], v234 offset1:1
	ds_read2_b32 v[6:7], v235 offset1:1
	ds_read2_b32 v[8:9], v236 offset1:1
	ds_read2_b32 v[10:11], v237 offset1:1
	ds_read2_b32 v[12:13], v238 offset1:1
	ds_read2_b32 v[192:193], v239 offset1:1
	ds_read2_b32 v[194:195], v240 offset1:1
	ds_read2_b32 v[202:203], v228 offset1:1
	ds_read2_b32 v[204:205], v229 offset1:1
	ds_read2_b32 v[220:221], v230 offset1:1
	ds_read2_b32 v[242:243], v231 offset1:1
	ds_read2_b32 v[244:245], v232 offset1:1
	ds_read2_b32 v[246:247], v233 offset1:1
	s_waitcnt lgkmcnt(9)
	v_pk_add_f32 v[164:165], v[164:165], v[10:11]
	v_pk_add_f32 v[162:163], v[162:163], v[6:7]
	ds_read2_b32 v[6:7], v225 offset1:1
	ds_read2_b32 v[10:11], v224 offset1:1
	s_waitcnt lgkmcnt(9)
	v_pk_add_f32 v[166:167], v[166:167], v[192:193]
	s_waitcnt lgkmcnt(2)
	v_pk_add_f32 v[174:175], v[174:175], v[246:247]
	v_pk_add_f32 v[172:173], v[172:173], v[244:245]
	v_pk_add_f32 v[170:171], v[170:171], v[220:221]
	v_pk_add_f32 v[168:169], v[168:169], v[202:203]
	v_pk_add_f32 v[160:161], v[160:161], v[2:3]
	v_pk_add_f32 v[150:151], v[150:151], v[194:195]
	v_pk_add_f32 v[148:149], v[148:149], v[12:13]
	v_pk_add_f32 v[146:147], v[146:147], v[8:9]
	s_waitcnt lgkmcnt(1)
	v_pk_add_f32 v[158:159], v[158:159], v[6:7]
	s_waitcnt lgkmcnt(0)
	v_pk_add_f32 v[156:157], v[156:157], v[10:11]
	v_pk_add_f32 v[154:155], v[154:155], v[242:243]
	v_pk_add_f32 v[152:153], v[152:153], v[204:205]
	v_pk_add_f32 v[144:145], v[144:145], v[4:5]
; #define RESC2(O, SL, a) do { if (__any((a) < 1.f)) { if (hi == 0) SL[r32] = (a); asm volatile("s_waitcnt lgkmcnt(0)" ::: "memory"); \
;     _Pragma("unroll") for (int d = 0; d < 4; ++d) _Pragma("unroll") for (int r = 0; r < 16; ++r) O[d][r] *= SL[crow(r, hi)]; } } while (0)
; __device__ __forceinline__ void softmax_tile(f32x16& p0, f32x16& p1, float& m, float& l, float& alpha, float cb, bf16x8& pa0, bf16x8& pa1, bf16x8& pa2, bf16x8& pa3) {
;   float mx_[4] = {p0[0], p0[1], p0[2], p0[3]};
; #pragma unroll
;   for (int r = 4; r < 16; ++r) mx_[r & 3] = fmaxf(mx_[r & 3], p0[r]);
; #pragma unroll
;   for (int r = 0; r < 16; ++r) mx_[r & 3] = fmaxf(mx_[r & 3], p1[r]);
;   float pmax = fmaxf(fmaxf(mx_[0], mx_[1]), fmaxf(mx_[2], mx_[3]));
;   { auto rr = __builtin_amdgcn_permlane32_swap(__float_as_uint(pmax), __float_as_uint(pmax), false, false);
;     pmax = fmaxf(__uint_as_float(rr[0]), __uint_as_float(rr[1])); }
;   pmax += cb;
;   float mn;
;   if (__builtin_expect(__all(pmax - m <= THR2), 1)) { mn = m; alpha = 1.f; }
;   else { mn = fmaxf(m, pmax); alpha = __builtin_amdgcn_exp2f(m - mn); m = mn; }
;   const float off = cb - mn;
; #pragma unroll
;   for (int r = 0; r < 16; ++r) p0[r] = __builtin_amdgcn_exp2f(p0[r] + off);
; #pragma unroll
;   for (int r = 0; r < 16; ++r) p1[r] = __builtin_amdgcn_exp2f(p1[r] + off);
;   float sm_[4] = {p0[0], p0[1], p0[2], p0[3]};
; #pragma unroll
;   for (int r = 4; r < 16; ++r) sm_[r & 3] += p0[r];
; #pragma unroll
;   for (int r = 0; r < 16; ++r) sm_[r & 3] += p1[r];
;   float ps = (sm_[0] + sm_[1]) + (sm_[2] + sm_[3]);
;   { auto rr = __builtin_amdgcn_permlane32_swap(__float_as_uint(ps), __float_as_uint(ps), false, false);
;     ps = __uint_as_float(rr[0]) + __uint_as_float(rr[1]); }
;   l = l * alpha + ps;
;     ...
;   PK4(p0, 0, pa0); PK4(p0, 8, pa1); PK4(p1, 0, pa2); PK4(p1, 8, pa3);
;     ...
; }
; __device__ __forceinline__ void attn_unit_A2(const bf16_t* __restrict__ Qb, int ldq, const bf16_t* __restrict__ Kh, int ldk, const bf16_t* __restrict__ Vh, int ldv, int nkeys, int q0, ...
;     ...
;     softmax_tile(s0, s1, m0, l0, al0, cb, pa0, pa1, pa2, pa3);
;     RESC2(oa, sl0, al0);
.LBB0_337:
	s_nop 4
	v_cndmask_b32_e64 v2, v197, 0, s[22:23]
	v_cndmask_b32_e64 v227, v207, v2, s[8:9]
	v_max_f32_e32 v2, v160, v164
	v_max_f32_e32 v3, v161, v165
	v_max_f32_e32 v4, v163, v167
	v_max3_f32 v5, v162, v166, v170
	v_max3_f32 v4, v4, v171, v175
	v_max3_f32 v2, v2, v168, v172
	v_max3_f32 v3, v3, v169, v173
	v_max3_f32 v5, v5, v174, v146
	v_max3_f32 v4, v4, v147, v151
	v_max3_f32 v2, v2, v144, v148
	v_max3_f32 v3, v3, v145, v149
	v_max3_f32 v5, v5, v150, v154
	v_max3_f32 v4, v4, v155, v159
	v_max3_f32 v2, v2, v152, v156
	v_max3_f32 v3, v3, v153, v157
	v_max3_f32 v4, v5, v158, v4
	v_max3_f32 v2, v2, v3, v4
	v_mov_b32_e32 v3, v2
	s_nop 1
	v_permlane32_swap_b32_e32 v2, v3
	v_max_f32_e32 v2, v2, v3
	v_add_f32_e32 v2, v227, v2
	v_sub_f32_e32 v3, v2, v0
	v_cmp_ge_f32_e32 vcc, s48, v3
	v_max_f32_e32 v2, v0, v2
	v_sub_f32_e32 v3, v0, v2
	v_exp_f32_e32 v3, v3
	s_cmp_eq_u64 vcc, exec
	s_cselect_b64 vcc, -1, 0
	v_cndmask_b32_e32 v0, v2, v0, vcc
	v_sub_f32_e32 v2, v227, v0
	v_cndmask_b32_e64 v15, v3, 1.0, vcc
	v_add_f32_e32 v3, v160, v2
	v_add_f32_e32 v4, v161, v2
	v_add_f32_e32 v5, v162, v2
	v_add_f32_e32 v6, v163, v2
	v_add_f32_e32 v7, v164, v2
	v_add_f32_e32 v8, v165, v2
	v_add_f32_e32 v9, v166, v2
	v_add_f32_e32 v10, v167, v2
	v_exp_f32_e32 v3, v3
	v_exp_f32_e32 v4, v4
	v_exp_f32_e32 v5, v5
	v_exp_f32_e32 v6, v6
	v_exp_f32_e32 v7, v7
	v_exp_f32_e32 v8, v8
	v_exp_f32_e32 v9, v9
	v_exp_f32_e32 v10, v10
	v_add_f32_e32 v11, v168, v2
	v_add_f32_e32 v12, v169, v2
	v_add_f32_e32 v13, v170, v2
	v_add_f32_e32 v160, v171, v2
	v_exp_f32_e32 v11, v11
	v_exp_f32_e32 v12, v12
	v_exp_f32_e32 v13, v13
	v_exp_f32_e32 v160, v160
	v_add_f32_e32 v161, v172, v2
	v_add_f32_e32 v162, v173, v2
	v_add_f32_e32 v163, v174, v2
	v_add_f32_e32 v164, v175, v2
	v_exp_f32_e32 v161, v161
	v_exp_f32_e32 v162, v162
	v_exp_f32_e32 v163, v163
	v_exp_f32_e32 v164, v164
	v_add_f32_e32 v144, v144, v2
	v_add_f32_e32 v145, v145, v2
	v_add_f32_e32 v146, v146, v2
	v_add_f32_e32 v147, v147, v2
	v_exp_f32_e32 v144, v144
	v_exp_f32_e32 v145, v145
	v_exp_f32_e32 v146, v146
	v_exp_f32_e32 v147, v147
	v_add_f32_e32 v148, v148, v2
	v_add_f32_e32 v149, v149, v2
	v_add_f32_e32 v150, v150, v2
	v_add_f32_e32 v151, v151, v2
	v_add_f32_e32 v152, v152, v2
	v_add_f32_e32 v153, v153, v2
	v_add_f32_e32 v154, v154, v2
	v_add_f32_e32 v155, v155, v2
	v_add_f32_e32 v156, v156, v2
	v_add_f32_e32 v157, v157, v2
	v_add_f32_e32 v158, v158, v2
	v_add_f32_e32 v2, v159, v2
	v_exp_f32_e32 v148, v148
	v_exp_f32_e32 v149, v149
	v_exp_f32_e32 v150, v150
	v_exp_f32_e32 v151, v151
	v_exp_f32_e32 v159, v2
	v_add_f32_e32 v2, v7, v3
	v_add_f32_e32 v165, v8, v4
	v_add_f32_e32 v166, v9, v5
	v_add_f32_e32 v167, v10, v6
	v_exp_f32_e32 v152, v152
	v_exp_f32_e32 v153, v153
	v_exp_f32_e32 v154, v154
	v_exp_f32_e32 v155, v155
	v_add_f32_e32 v2, v11, v2
	v_add_f32_e32 v165, v12, v165
	v_add_f32_e32 v166, v13, v166
	v_add_f32_e32 v167, v160, v167
	v_exp_f32_e32 v156, v156
	v_exp_f32_e32 v157, v157
	v_exp_f32_e32 v158, v158
	v_add_f32_e32 v2, v161, v2
	v_add_f32_e32 v165, v162, v165
	v_add_f32_e32 v166, v163, v166
	v_add_f32_e32 v167, v164, v167
	v_add_f32_e32 v2, v144, v2
	v_add_f32_e32 v165, v145, v165
	v_add_f32_e32 v166, v146, v166
	v_add_f32_e32 v167, v147, v167
	v_add_f32_e32 v2, v148, v2
	v_add_f32_e32 v165, v149, v165
	v_add_f32_e32 v166, v150, v166
	v_add_f32_e32 v167, v151, v167
	v_add_f32_e32 v2, v152, v2
	v_add_f32_e32 v165, v153, v165
	v_add_f32_e32 v166, v154, v166
	v_add_f32_e32 v167, v155, v167
	v_add_f32_e32 v2, v156, v2
	v_add_f32_e32 v165, v157, v165
	v_add_f32_e32 v166, v158, v166
	v_add_f32_e32 v167, v159, v167
	v_add_f32_e32 v2, v2, v165
	v_add_f32_e32 v165, v166, v167
	v_add_f32_e32 v220, v2, v165
	v_mov_b32_e32 v221, v220
	v_cvt_pk_bf16_f32 v2, v3, v4
	v_cvt_pk_bf16_f32 v3, v5, v6
	v_cvt_pk_bf16_f32 v4, v7, v8
	v_cvt_pk_bf16_f32 v5, v9, v10
	v_cvt_pk_bf16_f32 v6, v11, v12
	v_cvt_pk_bf16_f32 v7, v13, v160
	v_cvt_pk_bf16_f32 v8, v161, v162
	v_cvt_pk_bf16_f32 v9, v163, v164
	v_cvt_pk_bf16_f32 v10, v144, v145
	v_cvt_pk_bf16_f32 v11, v146, v147
	v_cvt_pk_bf16_f32 v12, v148, v149
	v_cvt_pk_bf16_f32 v13, v150, v151
	v_cvt_pk_bf16_f32 v144, v152, v153
	v_cvt_pk_bf16_f32 v145, v154, v155
	v_cvt_pk_bf16_f32 v146, v156, v157
	v_cvt_pk_bf16_f32 v147, v158, v159
	s_nop 1
	v_permlane32_swap_b32_e32 v220, v221
	v_permlane32_swap_b32_e32 v2, v4
	v_permlane32_swap_b32_e32 v3, v5
	v_permlane32_swap_b32_e32 v6, v8
	v_permlane32_swap_b32_e32 v7, v9
	v_permlane32_swap_b32_e32 v10, v12
	v_permlane32_swap_b32_e32 v11, v13
	v_permlane32_swap_b32_e32 v144, v146
	v_permlane32_swap_b32_e32 v145, v147
	v_cmp_gt_f32_e32 vcc, 1.0, v15
	s_cbranch_vccz .LBB0_341
	s_and_saveexec_b64 s[8:9], s[4:5]
	ds_write_b32 v215, v15
	s_or_b64 exec, exec, s[8:9]
	s_waitcnt lgkmcnt(0)
	ds_read_b128 v[148:151], v216 offset:96
	ds_read_b128 v[152:155], v216 offset:64
	ds_read_b128 v[156:159], v216 offset:32
	ds_read_b128 v[160:163], v216
	s_waitcnt lgkmcnt(3)
	v_pk_mul_f32 v[142:143], v[142:143], v[150:151]
	s_waitcnt lgkmcnt(2)
	v_pk_mul_f32 v[138:139], v[138:139], v[154:155]
	s_waitcnt lgkmcnt(1)
	v_pk_mul_f32 v[134:135], v[134:135], v[158:159]
	s_waitcnt lgkmcnt(0)
	v_pk_mul_f32 v[130:131], v[130:131], v[162:163]
	v_pk_mul_f32 v[140:141], v[140:141], v[148:149]
	v_pk_mul_f32 v[136:137], v[136:137], v[152:153]
	v_pk_mul_f32 v[132:133], v[132:133], v[156:157]
	v_pk_mul_f32 v[128:129], v[128:129], v[160:161]
	v_pk_mul_f32 v[110:111], v[110:111], v[150:151]
	v_pk_mul_f32 v[106:107], v[106:107], v[154:155]
	v_pk_mul_f32 v[102:103], v[102:103], v[158:159]
	v_pk_mul_f32 v[98:99], v[98:99], v[162:163]
	v_pk_mul_f32 v[108:109], v[108:109], v[148:149]
	v_pk_mul_f32 v[104:105], v[104:105], v[152:153]
	v_pk_mul_f32 v[100:101], v[100:101], v[156:157]
	v_pk_mul_f32 v[96:97], v[96:97], v[160:161]
	v_pk_mul_f32 v[62:63], v[62:63], v[150:151]
	v_pk_mul_f32 v[58:59], v[58:59], v[154:155]
	v_pk_mul_f32 v[54:55], v[54:55], v[158:159]
	v_pk_mul_f32 v[50:51], v[50:51], v[162:163]
	v_pk_mul_f32 v[60:61], v[60:61], v[148:149]
	v_pk_mul_f32 v[56:57], v[56:57], v[152:153]
	v_pk_mul_f32 v[52:53], v[52:53], v[156:157]
	v_pk_mul_f32 v[48:49], v[48:49], v[160:161]
	v_pk_mul_f32 v[94:95], v[94:95], v[150:151]
	v_pk_mul_f32 v[90:91], v[90:91], v[154:155]
	v_pk_mul_f32 v[86:87], v[86:87], v[158:159]
	v_pk_mul_f32 v[82:83], v[82:83], v[162:163]
	v_pk_mul_f32 v[92:93], v[92:93], v[148:149]
	v_pk_mul_f32 v[88:89], v[88:89], v[152:153]
	v_pk_mul_f32 v[84:85], v[84:85], v[156:157]
	v_pk_mul_f32 v[80:81], v[80:81], v[160:161]

; #define RESC2(O, SL, a) do { if (__any((a) < 1.f)) { if (hi == 0) SL[r32] = (a); asm volatile("s_waitcnt lgkmcnt(0)" ::: "memory"); \
;     _Pragma("unroll") for (int d = 0; d < 4; ++d) _Pragma("unroll") for (int r = 0; r < 16; ++r) O[d][r] *= SL[crow(r, hi)]; } } while (0)
; __device__ __forceinline__ void softmax_tile(f32x16& p0, f32x16& p1, float& m, float& l, float& alpha, float cb, bf16x8& pa0, bf16x8& pa1, bf16x8& pa2, bf16x8& pa3) {
;   float mx_[4] = {p0[0], p0[1], p0[2], p0[3]};
; #pragma unroll
;   for (int r = 4; r < 16; ++r) mx_[r & 3] = fmaxf(mx_[r & 3], p0[r]);
; #pragma unroll
;   for (int r = 0; r < 16; ++r) mx_[r & 3] = fmaxf(mx_[r & 3], p1[r]);
;   float pmax = fmaxf(fmaxf(mx_[0], mx_[1]), fmaxf(mx_[2], mx_[3]));
;   { auto rr = __builtin_amdgcn_permlane32_swap(__float_as_uint(pmax), __float_as_uint(pmax), false, false);
;     pmax = fmaxf(__uint_as_float(rr[0]), __uint_as_float(rr[1])); }
;   pmax += cb;
;   float mn;
;   if (__builtin_expect(__all(pmax - m <= THR2), 1)) { mn = m; alpha = 1.f; }
;   else { mn = fmaxf(m, pmax); alpha = __builtin_amdgcn_exp2f(m - mn); m = mn; }
;   const float off = cb - mn;
; #pragma unroll
;   for (int r = 0; r < 16; ++r) p0[r] = __builtin_amdgcn_exp2f(p0[r] + off);
; #pragma unroll
;   for (int r = 0; r < 16; ++r) p1[r] = __builtin_amdgcn_exp2f(p1[r] + off);
;   float sm_[4] = {p0[0], p0[1], p0[2], p0[3]};
; #pragma unroll
;   for (int r = 4; r < 16; ++r) sm_[r & 3] += p0[r];
; #pragma unroll
;   for (int r = 0; r < 16; ++r) sm_[r & 3] += p1[r];
;   float ps = (sm_[0] + sm_[1]) + (sm_[2] + sm_[3]);
;   { auto rr = __builtin_amdgcn_permlane32_swap(__float_as_uint(ps), __float_as_uint(ps), false, false);
;     ps = __uint_as_float(rr[0]) + __uint_as_float(rr[1]); }
;   l = l * alpha + ps;
;     ...
;   PK4(p0, 0, pa0); PK4(p0, 8, pa1); PK4(p1, 0, pa2); PK4(p1, 8, pa3);
;     ...
; }
; __device__ __forceinline__ void attn_unit_A2(const bf16_t* __restrict__ Qb, int ldq, const bf16_t* __restrict__ Kh, int ldk, const bf16_t* __restrict__ Vh, int ldv, int nkeys, int q0, ...
;     ...
;     softmax_tile(s0, s1, m1, l1, al1, cb, pa0, pa1, pa2, pa3);
;     RESC2(ob, sl1, al1);
.LBB0_343:
	s_nop 8
	v_max_f32_e32 v2, v160, v164
	v_max_f32_e32 v3, v161, v165
	v_max_f32_e32 v4, v163, v167
	v_max3_f32 v5, v162, v166, v170
	v_max3_f32 v4, v4, v171, v175
	v_max3_f32 v2, v2, v168, v172
	v_max3_f32 v3, v3, v169, v173
	v_max3_f32 v5, v5, v174, v146
	v_max3_f32 v4, v4, v147, v151
	v_max3_f32 v2, v2, v144, v148
	v_max3_f32 v3, v3, v145, v149
	v_max3_f32 v5, v5, v150, v154
	v_max3_f32 v4, v4, v155, v159
	v_max3_f32 v2, v2, v152, v156
	v_max3_f32 v3, v3, v153, v157
	v_max3_f32 v4, v5, v158, v4
	v_max3_f32 v2, v2, v3, v4
	v_mov_b32_e32 v3, v2
	s_nop 1
	v_permlane32_swap_b32_e32 v2, v3
	v_max_f32_e32 v2, v2, v3
	v_add_f32_e32 v2, v227, v2
	v_sub_f32_e32 v3, v2, v218
	v_cmp_ge_f32_e32 vcc, s48, v3
	s_cmp_eq_u64 vcc, exec
	v_max_f32_e32 v2, v218, v2
	s_cselect_b64 vcc, -1, 0
	v_sub_f32_e32 v3, v218, v2
	v_cndmask_b32_e32 v218, v2, v218, vcc
	v_sub_f32_e32 v2, v227, v218
	v_add_f32_e32 v148, v148, v2
	v_add_f32_e32 v8, v165, v2
	v_exp_f32_e32 v165, v148
	v_add_f32_e32 v148, v149, v2
	v_exp_f32_e32 v3, v3
	v_add_f32_e32 v9, v166, v2
	v_exp_f32_e32 v166, v148
	v_add_f32_e32 v148, v150, v2
	v_exp_f32_e32 v150, v148
	v_add_f32_e32 v148, v151, v2
	v_exp_f32_e32 v151, v148
	v_add_f32_e32 v148, v152, v2
	v_exp_f32_e32 v152, v148
	v_add_f32_e32 v148, v153, v2
	v_cndmask_b32_e64 v223, v3, 1.0, vcc
	v_add_f32_e32 v3, v160, v2
	v_add_f32_e32 v4, v161, v2
	v_add_f32_e32 v5, v162, v2
	v_add_f32_e32 v6, v163, v2
	v_add_f32_e32 v7, v164, v2
	v_add_f32_e32 v10, v167, v2
	v_exp_f32_e32 v153, v148
	v_add_f32_e32 v148, v154, v2
	v_exp_f32_e32 v3, v3
	v_exp_f32_e32 v4, v4
	v_exp_f32_e32 v5, v5
	v_exp_f32_e32 v6, v6
	v_exp_f32_e32 v7, v7
	v_exp_f32_e32 v8, v8
	v_exp_f32_e32 v9, v9
	v_exp_f32_e32 v10, v10
	v_add_f32_e32 v11, v168, v2
	v_add_f32_e32 v12, v169, v2
	v_add_f32_e32 v13, v170, v2
	v_add_f32_e32 v160, v171, v2
	v_exp_f32_e32 v154, v148
	v_add_f32_e32 v148, v155, v2
	v_exp_f32_e32 v11, v11
	v_exp_f32_e32 v12, v12
	v_exp_f32_e32 v13, v13
	v_exp_f32_e32 v160, v160
	v_add_f32_e32 v161, v172, v2
	v_add_f32_e32 v162, v173, v2
	v_add_f32_e32 v163, v174, v2
	v_add_f32_e32 v164, v175, v2
	v_exp_f32_e32 v155, v148
	v_add_f32_e32 v148, v156, v2
	v_exp_f32_e32 v161, v161
	v_exp_f32_e32 v162, v162
	v_exp_f32_e32 v163, v163
	v_exp_f32_e32 v164, v164
	v_add_f32_e32 v144, v144, v2
	v_add_f32_e32 v145, v145, v2
	v_add_f32_e32 v146, v146, v2
	v_add_f32_e32 v147, v147, v2
	v_exp_f32_e32 v156, v148
	v_add_f32_e32 v148, v157, v2
	v_exp_f32_e32 v144, v144
	v_exp_f32_e32 v145, v145
	v_exp_f32_e32 v146, v146
	v_exp_f32_e32 v147, v147
	v_exp_f32_e32 v157, v148
	v_add_f32_e32 v148, v158, v2
	v_add_f32_e32 v2, v159, v2
	v_exp_f32_e32 v158, v148
	v_exp_f32_e32 v159, v2
	v_add_f32_e32 v2, v7, v3
	v_add_f32_e32 v148, v8, v4
	v_add_f32_e32 v149, v9, v5
	v_add_f32_e32 v167, v10, v6
	v_add_f32_e32 v2, v11, v2
	v_add_f32_e32 v148, v12, v148
	v_add_f32_e32 v149, v13, v149
	v_add_f32_e32 v167, v160, v167
	v_add_f32_e32 v2, v161, v2
	v_add_f32_e32 v148, v162, v148
	v_add_f32_e32 v149, v163, v149
	v_add_f32_e32 v167, v164, v167
	v_add_f32_e32 v2, v144, v2
	v_add_f32_e32 v148, v145, v148
	v_add_f32_e32 v149, v146, v149
	v_add_f32_e32 v167, v147, v167
	v_add_f32_e32 v2, v165, v2
	v_add_f32_e32 v148, v166, v148
	v_add_f32_e32 v149, v150, v149
	v_add_f32_e32 v167, v151, v167
	v_add_f32_e32 v2, v152, v2
	v_add_f32_e32 v148, v153, v148
	v_add_f32_e32 v149, v154, v149
	v_add_f32_e32 v167, v155, v167
	v_add_f32_e32 v2, v156, v2
	v_add_f32_e32 v148, v157, v148
	v_add_f32_e32 v149, v158, v149
	v_add_f32_e32 v167, v159, v167
	v_add_f32_e32 v2, v2, v148
	v_add_f32_e32 v148, v149, v167
	v_add_f32_e32 v148, v2, v148
	v_mov_b32_e32 v149, v148
	v_cvt_pk_bf16_f32 v2, v3, v4
	v_cvt_pk_bf16_f32 v3, v5, v6
	v_cvt_pk_bf16_f32 v4, v7, v8
	v_cvt_pk_bf16_f32 v5, v9, v10
	v_cvt_pk_bf16_f32 v6, v11, v12
	v_cvt_pk_bf16_f32 v7, v13, v160
	v_cvt_pk_bf16_f32 v8, v161, v162
	v_cvt_pk_bf16_f32 v9, v163, v164
	v_cvt_pk_bf16_f32 v10, v144, v145
	v_cvt_pk_bf16_f32 v11, v146, v147
	v_cvt_pk_bf16_f32 v12, v165, v166
	v_cvt_pk_bf16_f32 v13, v150, v151
	v_cvt_pk_bf16_f32 v144, v152, v153
	v_cvt_pk_bf16_f32 v145, v154, v155
	v_cvt_pk_bf16_f32 v146, v156, v157
	v_cvt_pk_bf16_f32 v147, v158, v159
	s_nop 1
	v_permlane32_swap_b32_e32 v148, v149
	v_permlane32_swap_b32_e32 v2, v4
	v_permlane32_swap_b32_e32 v3, v5
	v_permlane32_swap_b32_e32 v6, v8
	v_permlane32_swap_b32_e32 v7, v9
	v_permlane32_swap_b32_e32 v10, v12
	v_permlane32_swap_b32_e32 v11, v13
	v_permlane32_swap_b32_e32 v144, v146
	v_permlane32_swap_b32_e32 v145, v147
	v_cmp_gt_f32_e32 vcc, 1.0, v223
	s_cbranch_vccz .LBB0_347
	s_and_saveexec_b64 s[6:7], s[4:5]
	ds_write_b32 v215, v223 offset:128
	s_or_b64 exec, exec, s[6:7]
	s_waitcnt lgkmcnt(0)
	ds_read_b128 v[150:153], v216 offset:224
	ds_read_b128 v[154:157], v216 offset:192
	ds_read_b128 v[158:161], v216 offset:160
	ds_read_b128 v[162:165], v216 offset:128
	s_waitcnt lgkmcnt(3)
	v_pk_mul_f32 v[126:127], v[126:127], v[152:153]
	s_waitcnt lgkmcnt(2)
	v_pk_mul_f32 v[122:123], v[122:123], v[156:157]
	s_waitcnt lgkmcnt(1)
	v_pk_mul_f32 v[118:119], v[118:119], v[160:161]
	s_waitcnt lgkmcnt(0)
	v_pk_mul_f32 v[114:115], v[114:115], v[164:165]
	v_pk_mul_f32 v[124:125], v[124:125], v[150:151]
	v_pk_mul_f32 v[120:121], v[120:121], v[154:155]
	v_pk_mul_f32 v[116:117], v[116:117], v[158:159]
	v_pk_mul_f32 v[112:113], v[112:113], v[162:163]
	v_pk_mul_f32 v[78:79], v[78:79], v[152:153]
	v_pk_mul_f32 v[74:75], v[74:75], v[156:157]
	v_pk_mul_f32 v[70:71], v[70:71], v[160:161]
	v_pk_mul_f32 v[66:67], v[66:67], v[164:165]
	v_pk_mul_f32 v[76:77], v[76:77], v[150:151]
	v_pk_mul_f32 v[72:73], v[72:73], v[154:155]
	v_pk_mul_f32 v[68:69], v[68:69], v[158:159]
	v_pk_mul_f32 v[64:65], v[64:65], v[162:163]
	v_pk_mul_f32 v[30:31], v[30:31], v[152:153]
	v_pk_mul_f32 v[26:27], v[26:27], v[156:157]
	v_pk_mul_f32 v[22:23], v[22:23], v[160:161]
	v_pk_mul_f32 v[18:19], v[18:19], v[164:165]
	v_pk_mul_f32 v[28:29], v[28:29], v[150:151]
	v_pk_mul_f32 v[24:25], v[24:25], v[154:155]
	v_pk_mul_f32 v[20:21], v[20:21], v[158:159]
	v_pk_mul_f32 v[16:17], v[16:17], v[162:163]
	v_pk_mul_f32 v[46:47], v[46:47], v[152:153]
	v_pk_mul_f32 v[42:43], v[42:43], v[156:157]
	v_pk_mul_f32 v[38:39], v[38:39], v[160:161]
	v_pk_mul_f32 v[34:35], v[34:35], v[164:165]
	v_pk_mul_f32 v[44:45], v[44:45], v[150:151]
	v_pk_mul_f32 v[40:41], v[40:41], v[154:155]
	v_pk_mul_f32 v[36:37], v[36:37], v[158:159]
	v_pk_mul_f32 v[32:33], v[32:33], v[162:163]
